# M2 scan step: A fragments as single ds_read_b128 from k-permuted LDS tiles; next step uv loads kept in flight across the MFMA work (shift/mask deferred to loop bottom, vmcnt 16); on top of batched pro
# speedup vs baseline: 1.0190x; 1.0071x over previous
.LBB0_1032:
	s_bitcmp1_b32 s61, 0
	s_cselect_b32 s4, 0xf600, 0
	s_add_i32 s65, s4, 0
	v_and_b32_e32 v80, 3, v201
	v_lshlrev_b32_e32 v80, 3, v80
	v_mov_b32_e32 v81, 0xf8e81000
	v_lshrrev_b32_e32 v80, v80, v81
	v_bfe_i32 v80, v80, 0, 8
	v_lshl_add_u32 v77, v208, 1, s65
	v_lshl_add_u32 v78, v209, 1, s65
	v_lshl_add_u32 v76, v154, 1, v77
	v_add_u32_e32 v76, v76, v80
	v_add_u32_e32 v84, 0x4400, v76
	v_lshl_add_u32 v79, v109, 1, v78
	v_add_u32_e32 v79, v79, v80
	v_add_u32_e32 v82, 0x8800, v79
	s_mov_b64 s[4:5], -1
	s_and_b64 vcc, exec, s[40:41]
	v_lshl_add_u32 v77, v215, 1, v77
	v_add_u32_e32 v77, v77, v80
	v_add_u32_e32 v85, 0x4400, v77
	v_lshl_add_u32 v78, v216, 1, v78
	v_add_u32_e32 v78, v78, v80
	v_add_u32_e32 v83, 0x8800, v78
	s_waitcnt vmcnt(21)
	ds_write2_b64 v76, v[32:33], v[34:35] offset1:2
	s_waitcnt vmcnt(20)
	ds_write2_b64 v82, v[36:37], v[38:39] offset1:2
	s_cbranch_vccz .LBB0_1034
	s_waitcnt vmcnt(19)
	ds_write2_b64 v77, v[40:41], v[42:43] offset1:2
	s_waitcnt vmcnt(18)
	ds_write2_b64 v83, v[44:45], v[46:47] offset1:2
	s_mov_b64 s[4:5], 0
.LBB0_1034:
	s_andn2_b64 vcc, exec, s[4:5]
	s_cbranch_vccnz .LBB0_1036
	s_waitcnt vmcnt(17)
	ds_write2_b64 v84, v[52:53], v[54:55] offset1:2
	ds_write2_b64 v77, v[40:41], v[42:43] offset1:2
	ds_write2_b64 v83, v[44:45], v[46:47] offset1:2
	s_waitcnt vmcnt(16)
	ds_write2_b64 v85, v[56:57], v[58:59] offset1:2
.LBB0_1036:
	v_lshlrev_b32_e32 v76, 1, v109
	v_add3_u32 v76, s65, v76, v114
	v_add_u32_e32 v76, v76, v80
	v_add_u32_e32 v76, 0xd000, v76
	s_waitcnt vmcnt(17)
	ds_write2_b64 v76, v[48:49], v[50:51] offset1:2
	s_and_saveexec_b64 s[4:5], s[0:1]
	s_cbranch_execz .LBB0_1038
	v_lshl_add_u32 v76, v201, 2, s65
	s_waitcnt vmcnt(16)
	ds_write_b32 v76, v210 offset:62464

.LBB0_1043:
	s_ashr_i32 s87, s86, 31
	s_lshl_b64 s[70:71], s[86:87], 14
	s_lshl_b64 s[68:69], s[86:87], 13
	v_lshl_add_u64 v[40:41], v[166:167], 0, s[70:71]
	v_lshl_add_u64 v[42:43], v[172:173], 0, s[70:71]
	v_lshl_add_u64 v[32:33], v[116:117], 1, v[40:41]
	v_lshl_add_u64 v[36:37], v[118:119], 1, v[42:43]
	v_lshl_add_u64 v[40:41], v[120:121], 1, v[40:41]
	v_lshl_add_u64 v[44:45], v[122:123], 1, v[42:43]
	v_lshl_add_u64 v[48:49], v[174:175], 0, s[68:69]
	s_lshl_b64 s[68:69], s[86:87], 9
	global_load_dwordx4 v[32:35], v[32:33], off
	s_nop 0
	global_load_dwordx4 v[36:39], v[36:37], off
	s_nop 0
	global_load_dwordx4 v[40:43], v[40:41], off
	s_nop 0
	global_load_dwordx4 v[44:47], v[44:45], off
	v_lshl_add_u64 v[76:77], v[176:177], 0, s[68:69]
	global_load_dwordx4 v[48:51], v[48:49], off
	s_nop 0
	global_load_dword v210, v[76:77], off
	s_mov_b64 s[86:87], -1
	s_and_b64 vcc, exec, s[40:41]
	s_cbranch_vccz .LBB0_1045
	s_and_b64 s[68:69], s[4:5], exec
	v_add_u32_e32 v76, 64, v211
	s_cselect_b32 s67, 64, 32
	v_cndmask_b32_e64 v92, v142, v76, s[4:5]
	s_add_i32 s4, s67, -1
	v_min_i32_e32 v76, s4, v200
	v_add_u32_e32 v78, v76, v92
	v_lshrrev_b32_e32 v76, 8, v78
	v_lshlrev_b32_e32 v78, 9, v78
	v_mul_i32_i24_e32 v76, 60, v76
	v_and_b32_e32 v100, 0x1fe00, v78
	v_min_i32_e32 v78, s4, v105
	v_ashrrev_i32_e32 v77, 31, v76
	v_add_u32_e32 v80, v78, v92
	v_lshlrev_b64 v[76:77], 17, v[76:77]
	v_lshrrev_b32_e32 v78, 8, v80
	v_lshl_add_u64 v[76:77], s[10:11], 0, v[76:77]
	v_mul_i32_i24_e32 v78, 60, v78
	v_lshlrev_b32_e32 v80, 9, v80
	v_lshl_add_u64 v[76:77], v[76:77], 0, v[100:101]
	v_ashrrev_i32_e32 v79, 31, v78
	v_and_b32_e32 v100, 0x1fe00, v80
	v_min_i32_e32 v80, s4, v202
	v_lshlrev_b64 v[78:79], 17, v[78:79]
	v_add_u32_e32 v82, v80, v92
	v_lshl_add_u64 v[78:79], s[10:11], 0, v[78:79]
	v_lshrrev_b32_e32 v80, 8, v82
	v_lshlrev_b32_e32 v82, 9, v82
	v_lshl_add_u64 v[78:79], v[78:79], 0, v[100:101]
	v_mul_i32_i24_e32 v80, 60, v80
	v_and_b32_e32 v100, 0x1fe00, v82
	v_min_i32_e32 v82, s4, v203
	v_ashrrev_i32_e32 v81, 31, v80
	v_add_u32_e32 v84, v82, v92
	v_lshlrev_b64 v[80:81], 17, v[80:81]
	v_lshrrev_b32_e32 v82, 8, v84
	v_lshl_add_u64 v[80:81], s[10:11], 0, v[80:81]
	v_mul_i32_i24_e32 v82, 60, v82
	v_lshlrev_b32_e32 v84, 9, v84
	v_lshl_add_u64 v[80:81], v[80:81], 0, v[100:101]
	v_ashrrev_i32_e32 v83, 31, v82
	v_and_b32_e32 v100, 0x1fe00, v84
	v_min_i32_e32 v84, s4, v204
	v_lshlrev_b64 v[82:83], 17, v[82:83]
	v_add_u32_e32 v86, v84, v92
	v_lshl_add_u64 v[82:83], s[10:11], 0, v[82:83]
	v_lshrrev_b32_e32 v84, 8, v86
	v_lshlrev_b32_e32 v86, 9, v86
	v_lshl_add_u64 v[82:83], v[82:83], 0, v[100:101]
	v_mul_i32_i24_e32 v84, 60, v84
	v_and_b32_e32 v100, 0x1fe00, v86
	v_min_i32_e32 v86, s4, v205
	v_ashrrev_i32_e32 v85, 31, v84
	v_add_u32_e32 v88, v86, v92
	v_lshlrev_b64 v[84:85], 17, v[84:85]
	v_lshrrev_b32_e32 v86, 8, v88
	v_lshl_add_u64 v[84:85], s[10:11], 0, v[84:85]
	v_mul_i32_i24_e32 v86, 60, v86
	v_lshlrev_b32_e32 v88, 9, v88
	v_lshl_add_u64 v[84:85], v[84:85], 0, v[100:101]
	v_ashrrev_i32_e32 v87, 31, v86
	v_and_b32_e32 v100, 0x1fe00, v88
	v_min_i32_e32 v88, s4, v206
	v_lshlrev_b64 v[86:87], 17, v[86:87]
	v_add_u32_e32 v90, v88, v92
	v_lshl_add_u64 v[86:87], s[10:11], 0, v[86:87]
	v_lshrrev_b32_e32 v88, 8, v90
	v_lshlrev_b32_e32 v90, 9, v90
	v_lshl_add_u64 v[86:87], v[86:87], 0, v[100:101]
	v_and_b32_e32 v100, 0x1fe00, v90
	v_min_i32_e32 v90, s4, v207
	v_add_u32_e32 v93, v90, v92
	v_mul_i32_i24_e32 v88, 60, v88
	v_lshrrev_b32_e32 v90, 8, v93
	v_ashrrev_i32_e32 v89, 31, v88
	v_mul_i32_i24_e32 v90, 60, v90
	v_lshlrev_b64 v[88:89], 17, v[88:89]
	v_ashrrev_i32_e32 v91, 31, v90
	v_lshl_add_u64 v[88:89], s[10:11], 0, v[88:89]
	v_lshlrev_b64 v[90:91], 17, v[90:91]
	v_lshlrev_b32_e32 v93, 9, v93
	v_lshl_add_u64 v[88:89], v[88:89], 0, v[100:101]
	v_lshl_add_u64 v[90:91], s[10:11], 0, v[90:91]
	v_and_b32_e32 v100, 0x1fe00, v93
	v_lshl_add_u64 v[90:91], v[90:91], 0, v[100:101]
	v_lshl_add_u64 v[76:77], v[76:77], 0, v[128:129]
	v_lshl_add_u64 v[90:91], v[90:91], 0, v[128:129]
	v_lshl_add_u64 v[76:77], v[76:77], 0, v[170:171]
	v_lshl_add_u64 v[78:79], v[78:79], 0, v[128:129]
	v_lshl_add_u64 v[80:81], v[80:81], 0, v[128:129]
	v_lshl_add_u64 v[82:83], v[82:83], 0, v[128:129]
	v_lshl_add_u64 v[84:85], v[84:85], 0, v[128:129]
	v_lshl_add_u64 v[86:87], v[86:87], 0, v[128:129]
	v_lshl_add_u64 v[88:89], v[88:89], 0, v[128:129]
	v_lshl_add_u64 v[90:91], v[90:91], 0, v[170:171]
	v_lshl_add_u64 v[78:79], v[78:79], 0, v[170:171]
	v_lshl_add_u64 v[80:81], v[80:81], 0, v[170:171]
	v_lshl_add_u64 v[82:83], v[82:83], 0, v[170:171]
	v_lshl_add_u64 v[84:85], v[84:85], 0, v[170:171]
	v_lshl_add_u64 v[86:87], v[86:87], 0, v[170:171]
	v_lshl_add_u64 v[88:89], v[88:89], 0, v[170:171]
	global_load_ushort v184, v[76:77], off
	global_load_ushort v185, v[78:79], off
	global_load_ushort v186, v[80:81], off
	global_load_ushort v187, v[82:83], off
	global_load_ushort v192, v[84:85], off
	global_load_ushort v193, v[86:87], off
	global_load_ushort v194, v[88:89], off
	s_nop 0
	global_load_ushort v195, v[90:91], off
	v_min_i32_e32 v76, s4, v108
	v_add_u32_e32 v78, v76, v92
	v_lshrrev_b32_e32 v76, 8, v78
	v_mul_i32_i24_e32 v76, 60, v76
	v_lshlrev_b32_e32 v78, 9, v78
	v_ashrrev_i32_e32 v77, 31, v76
	v_and_b32_e32 v100, 0x1fe00, v78
	v_min_i32_e32 v78, s4, v143
	v_lshlrev_b64 v[76:77], 17, v[76:77]
	v_add_u32_e32 v80, v78, v92
	v_lshl_add_u64 v[76:77], s[10:11], 0, v[76:77]
	v_lshrrev_b32_e32 v78, 8, v80
	v_lshlrev_b32_e32 v80, 9, v80
	v_lshl_add_u64 v[76:77], v[76:77], 0, v[100:101]
	v_mul_i32_i24_e32 v78, 60, v78
	v_and_b32_e32 v100, 0x1fe00, v80
	v_min_i32_e32 v80, s4, v106
	v_ashrrev_i32_e32 v79, 31, v78
	v_add_u32_e32 v82, v80, v92
	v_lshlrev_b64 v[78:79], 17, v[78:79]
	v_lshrrev_b32_e32 v80, 8, v82
	v_lshl_add_u64 v[78:79], s[10:11], 0, v[78:79]
	v_mul_i32_i24_e32 v80, 60, v80
	v_lshlrev_b32_e32 v82, 9, v82
	v_lshl_add_u64 v[78:79], v[78:79], 0, v[100:101]
	v_ashrrev_i32_e32 v81, 31, v80
	v_and_b32_e32 v100, 0x1fe00, v82
	v_min_i32_e32 v82, s4, v107
	v_lshlrev_b64 v[80:81], 17, v[80:81]
	v_add_u32_e32 v84, v82, v92
	v_lshl_add_u64 v[80:81], s[10:11], 0, v[80:81]
	v_lshrrev_b32_e32 v82, 8, v84
	v_lshlrev_b32_e32 v84, 9, v84
	v_lshl_add_u64 v[80:81], v[80:81], 0, v[100:101]
	v_mul_i32_i24_e32 v82, 60, v82
	v_and_b32_e32 v100, 0x1fe00, v84
	v_min_i32_e32 v84, s4, v112
	v_ashrrev_i32_e32 v83, 31, v82
	v_add_u32_e32 v86, v84, v92
	v_lshlrev_b64 v[82:83], 17, v[82:83]
	v_lshrrev_b32_e32 v84, 8, v86
	v_lshl_add_u64 v[82:83], s[10:11], 0, v[82:83]
	v_mul_i32_i24_e32 v84, 60, v84
	v_lshlrev_b32_e32 v86, 9, v86
	v_lshl_add_u64 v[82:83], v[82:83], 0, v[100:101]
	v_ashrrev_i32_e32 v85, 31, v84
	v_and_b32_e32 v100, 0x1fe00, v86
	v_min_i32_e32 v86, s4, v155
	v_lshlrev_b64 v[84:85], 17, v[84:85]
	v_add_u32_e32 v88, v86, v92
	v_lshl_add_u64 v[84:85], s[10:11], 0, v[84:85]
	v_lshrrev_b32_e32 v86, 8, v88
	v_lshlrev_b32_e32 v88, 9, v88
	v_lshl_add_u64 v[84:85], v[84:85], 0, v[100:101]
	v_and_b32_e32 v100, 0x1fe00, v88
	v_min_i32_e32 v88, s4, v110
	v_add_u32_e32 v91, v88, v92
	v_mul_i32_i24_e32 v86, 60, v86
	v_lshrrev_b32_e32 v88, 8, v91
	v_ashrrev_i32_e32 v87, 31, v86
	v_mul_i32_i24_e32 v88, 60, v88
	v_lshlrev_b64 v[86:87], 17, v[86:87]
	v_ashrrev_i32_e32 v89, 31, v88
	v_lshl_add_u64 v[86:87], s[10:11], 0, v[86:87]
	v_lshlrev_b64 v[88:89], 17, v[88:89]
	v_lshlrev_b32_e32 v91, 9, v91
	v_lshl_add_u64 v[86:87], v[86:87], 0, v[100:101]
	v_lshl_add_u64 v[88:89], s[10:11], 0, v[88:89]
	v_and_b32_e32 v100, 0x1fe00, v91
	v_lshl_add_u64 v[88:89], v[88:89], 0, v[100:101]
	v_lshl_add_u64 v[76:77], v[76:77], 0, v[128:129]
	v_lshl_add_u64 v[78:79], v[78:79], 0, v[128:129]
	v_lshl_add_u64 v[80:81], v[80:81], 0, v[128:129]
	v_lshl_add_u64 v[84:85], v[84:85], 0, v[128:129]
	v_lshl_add_u64 v[88:89], v[88:89], 0, v[128:129]
	v_lshl_add_u64 v[76:77], v[76:77], 0, v[170:171]
	v_lshl_add_u64 v[78:79], v[78:79], 0, v[170:171]
	v_lshl_add_u64 v[80:81], v[80:81], 0, v[170:171]
	v_lshl_add_u64 v[84:85], v[84:85], 0, v[170:171]
	v_lshl_add_u64 v[88:89], v[88:89], 0, v[170:171]
	global_load_ushort v189, v[78:79], off
	s_nop 0
	global_load_ushort v198, v[88:89], off
	s_nop 0
	global_load_ushort v196, v[84:85], off
	s_nop 0
	global_load_ushort v190, v[80:81], off
	s_nop 0
	global_load_ushort v188, v[76:77], off
	v_lshl_add_u64 v[76:77], v[82:83], 0, v[128:129]
	v_lshl_add_u64 v[78:79], v[86:87], 0, v[128:129]
	v_lshl_add_u64 v[76:77], v[76:77], 0, v[170:171]
	v_lshl_add_u64 v[78:79], v[78:79], 0, v[170:171]
	global_load_ushort v191, v[76:77], off
	s_nop 0
	global_load_ushort v197, v[78:79], off
	v_min_i32_e32 v76, s4, v111
	v_add_u32_e32 v79, v76, v92
	v_lshrrev_b32_e32 v76, 8, v79
	v_mul_i32_i24_e32 v76, 60, v76
	v_ashrrev_i32_e32 v77, 31, v76
	v_lshlrev_b64 v[76:77], 17, v[76:77]
	v_lshlrev_b32_e32 v79, 9, v79
	v_lshl_add_u64 v[76:77], s[10:11], 0, v[76:77]
	v_and_b32_e32 v100, 0x1fe00, v79
	v_lshl_add_u64 v[76:77], v[76:77], 0, v[100:101]
	v_lshl_add_u64 v[76:77], v[76:77], 0, v[128:129]
	v_lshl_add_u64 v[76:77], v[76:77], 0, v[170:171]
	global_load_ushort v199, v[76:77], off
	s_mov_b64 s[86:87], 0
.LBB0_1045:
	s_andn2_b64 vcc, exec, s[86:87]
	s_cbranch_vccnz .LBB0_1048
	s_ashr_i32 s85, s84, 31
	s_lshl_b64 s[4:5], s[84:85], 14
	v_lshl_add_u64 v[52:53], v[168:169], 0, s[4:5]
	s_add_u32 s4, s52, s4
	s_addc_u32 s5, s53, s5
	v_lshl_add_u64 v[54:55], v[116:117], 1, v[52:53]
	s_waitcnt vmcnt(22)
	v_lshl_add_u64 v[56:57], v[120:121], 1, v[52:53]
	v_lshl_add_u64 v[52:53], v[124:125], 1, s[4:5]
	v_lshl_add_u64 v[58:59], v[126:127], 1, s[4:5]
	v_lshl_add_u64 v[76:77], v[130:131], 1, s[4:5]
	v_lshl_add_u64 v[78:79], v[132:133], 1, s[4:5]
	v_lshl_add_u64 v[80:81], v[134:135], 1, s[4:5]
	v_lshl_add_u64 v[82:83], v[136:137], 1, s[4:5]
	v_lshl_add_u64 v[84:85], v[138:139], 1, s[4:5]
	v_lshl_add_u64 v[86:87], v[140:141], 1, s[4:5]
	global_load_ushort v184, v[52:53], off
	global_load_ushort v185, v[58:59], off
	global_load_ushort v186, v[76:77], off
	global_load_ushort v187, v[78:79], off
	global_load_ushort v192, v[80:81], off
	global_load_ushort v193, v[82:83], off
	global_load_ushort v194, v[84:85], off
	global_load_ushort v195, v[86:87], off
	v_lshl_add_u64 v[52:53], v[144:145], 1, s[4:5]
	v_lshl_add_u64 v[58:59], v[146:147], 1, s[4:5]
	v_lshl_add_u64 v[76:77], v[148:149], 1, s[4:5]
	v_lshl_add_u64 v[78:79], v[150:151], 1, s[4:5]
	v_lshl_add_u64 v[80:81], v[152:153], 1, s[4:5]
	v_lshl_add_u64 v[82:83], v[156:157], 1, s[4:5]
	v_lshl_add_u64 v[84:85], v[158:159], 1, s[4:5]
	v_lshl_add_u64 v[86:87], v[160:161], 1, s[4:5]
	global_load_ushort v188, v[52:53], off
	global_load_ushort v189, v[58:59], off
	s_nop 0
	global_load_ushort v190, v[76:77], off
	s_nop 0
	global_load_ushort v191, v[78:79], off
	s_nop 0
	global_load_ushort v196, v[80:81], off
	global_load_ushort v197, v[82:83], off
	s_nop 0
	global_load_ushort v198, v[84:85], off
	global_load_ushort v199, v[86:87], off
	s_nop 0
	global_load_dwordx4 v[52:55], v[54:55], off
	s_nop 0
	global_load_dwordx4 v[56:59], v[56:57], off
	s_branch .LBB0_1048

.LBB0_1050:
.LBB0_1051:
	v_lshlrev_b32_e32 v76, 2, v200
	v_lshlrev_b32_e32 v77, 1, v113
	v_add3_u32 v100, s65, v76, v77
	v_add_u32_e32 v222, 0x4000, v100
	v_add_u32_e32 v238, 0x5000, v100
	ds_read_b128 v[76:79], v222 offset:1024
	ds_read_b128 v[80:83], v222 offset:1088
	ds_read_b128 v[218:221], v222 offset:1152
	ds_read_b128 v[222:225], v222 offset:1216
	ds_read_b128 v[226:229], v238 offset:1280
	ds_read_b128 v[230:233], v238 offset:1344
	ds_read_b128 v[234:237], v238 offset:1408
	ds_read_b128 v[238:241], v238 offset:1472
	s_waitcnt lgkmcnt(7)
	v_mfma_f32_16x16x32_bf16 v[68:71], v[76:79], v[84:87], v[68:71]
	s_waitcnt lgkmcnt(3)
	v_mfma_f32_16x16x32_bf16 v[72:75], v[226:229], v[84:87], v[72:75]
	v_mfma_f32_16x16x32_bf16 v[68:71], v[80:83], v[88:91], v[68:71]
	s_waitcnt lgkmcnt(2)
	v_mfma_f32_16x16x32_bf16 v[72:75], v[230:233], v[88:91], v[72:75]
	v_mfma_f32_16x16x32_bf16 v[68:71], v[218:221], v[92:95], v[68:71]
	s_waitcnt lgkmcnt(1)
	v_mfma_f32_16x16x32_bf16 v[72:75], v[234:237], v[92:95], v[72:75]
	v_mfma_f32_16x16x32_bf16 v[68:71], v[222:225], v[96:99], v[68:71]
	s_waitcnt lgkmcnt(0)
	v_mfma_f32_16x16x32_bf16 v[72:75], v[238:241], v[96:99], v[72:75]
	v_add_u32_e32 v222, 0x6000, v100
	v_add_u32_e32 v100, 0x7000, v100
	ds_read_b128 v[76:79], v222 offset:1536
	ds_read_b128 v[80:83], v222 offset:1600
	ds_read_b128 v[218:221], v222 offset:1664
	ds_read_b128 v[222:225], v222 offset:1728
	ds_read_b128 v[226:229], v100 offset:1792
	ds_read_b128 v[230:233], v100 offset:1856
	ds_read_b128 v[234:237], v100 offset:1920
	ds_read_b128 v[238:241], v100 offset:1984
	s_waitcnt lgkmcnt(7)
	v_mfma_f32_16x16x32_bf16 v[60:63], v[76:79], v[84:87], v[60:63]
	s_waitcnt lgkmcnt(3)
	v_mfma_f32_16x16x32_bf16 v[64:67], v[226:229], v[84:87], v[64:67]
	v_mfma_f32_16x16x32_bf16 v[60:63], v[80:83], v[88:91], v[60:63]
	s_waitcnt lgkmcnt(2)
	v_mfma_f32_16x16x32_bf16 v[64:67], v[230:233], v[88:91], v[64:67]
	v_mfma_f32_16x16x32_bf16 v[60:63], v[218:221], v[92:95], v[60:63]
	s_waitcnt lgkmcnt(1)
	v_mfma_f32_16x16x32_bf16 v[64:67], v[234:237], v[92:95], v[64:67]
	v_mfma_f32_16x16x32_bf16 v[60:63], v[222:225], v[96:99], v[60:63]
	s_waitcnt lgkmcnt(0)
	v_mfma_f32_16x16x32_bf16 v[64:67], v[238:241], v[96:99], v[64:67]
	v_cvt_pk_bf16_f32 v76, v68, v69
	v_cvt_pk_bf16_f32 v77, v70, v71
	v_cvt_pk_bf16_f32 v78, v72, v73
	v_cvt_pk_bf16_f32 v79, v74, v75
	v_cvt_pk_bf16_f32 v80, v60, v61
	v_cvt_pk_bf16_f32 v81, v62, v63
	v_cvt_pk_bf16_f32 v82, v64, v65
	v_cvt_pk_bf16_f32 v83, v66, v67
.LBB0_1052:
	v_lshl_add_u32 v252, v200, 2, s65
	v_lshl_add_u32 v226, v113, 1, v252
	v_add_u32_e32 v218, v226, v213
	v_add_u32_e32 v222, 0xd000, v218
	v_add_u32_e32 v238, 0x1000, v226
	s_nop 0
	ds_read_b128 v[60:63], v226
	s_nop 0
	ds_read_b128 v[64:67], v226 offset:64
	ds_read_b128 v[68:71], v226 offset:128
	ds_read_b128 v[72:75], v226 offset:192
	ds_read_b128 v[218:221], v222
	ds_read_b128 v[222:225], v222 offset:64
	ds_read_b128 v[226:229], v238 offset:256
	ds_read_b128 v[230:233], v238 offset:320
	ds_read_b128 v[234:237], v238 offset:384
	ds_read_b128 v[238:241], v238 offset:448
	v_add_u32_e32 v253, v252, v115
	v_add_u32_e32 v246, 0xd000, v253
	ds_read_b128 v[242:245], v246
	ds_read_b128 v[246:249], v246 offset:64
	s_cmpk_lt_i32 s66, 0x80
	v_subrev_u32_e32 v100, 32, v142
	s_cselect_b64 vcc, -1, 0
	v_cndmask_b32_e32 v100, v100, v211, vcc
	v_or_b32_e32 v250, v100, v200
	s_waitcnt lgkmcnt(11)
	v_mfma_f32_16x16x32_bf16 v[60:63], v[60:63], v[84:87], 0
	v_ashrrev_i32_e32 v251, 31, v250
	s_waitcnt lgkmcnt(10)
	v_mfma_f32_16x16x32_bf16 v[60:63], v[64:67], v[88:91], v[60:63]
	v_lshlrev_b64 v[64:65], 14, v[250:251]
	s_waitcnt lgkmcnt(9)
	v_mfma_f32_16x16x32_bf16 v[60:63], v[68:71], v[92:95], v[60:63]
	v_lshl_add_u64 v[68:69], v[182:183], 0, v[64:65]
	v_add_co_u32_e64 v70, s[4:5], s56, v68
	s_waitcnt lgkmcnt(5)
	v_mfma_f32_16x16x32_bf16 v[226:229], v[226:229], v[84:87], 0
	v_addc_co_u32_e64 v71, s[4:5], 0, v69, s[4:5]
	v_mfma_f32_16x16x32_bf16 v[60:63], v[72:75], v[96:99], v[60:63]
	v_mfma_f32_16x16x32_bf16 v[60:63], v[218:221], v[76:79], v[60:63]
	s_waitcnt lgkmcnt(4)
	v_mfma_f32_16x16x32_bf16 v[64:67], v[230:233], v[88:91], v[226:229]
	v_mfma_f32_16x16x32_bf16 v[60:63], v[222:225], v[80:83], v[60:63]
	s_waitcnt lgkmcnt(3)
	v_mfma_f32_16x16x32_bf16 v[64:67], v[234:237], v[92:95], v[64:67]
	s_waitcnt lgkmcnt(2)
	v_mfma_f32_16x16x32_bf16 v[64:67], v[238:241], v[96:99], v[64:67]
	s_nop 3
	global_store_dword v[68:69], v60, off
	v_add_co_u32_e64 v60, s[4:5], s57, v68
	global_store_dword v[70:71], v61, off
	s_nop 0
	v_addc_co_u32_e64 v61, s[4:5], 0, v69, s[4:5]
	global_store_dword v[60:61], v62, off
	v_add_co_u32_e64 v60, s[4:5], s58, v68
	v_or_b32_e32 v68, 16, v250
	s_nop 0
	v_addc_co_u32_e64 v61, s[4:5], 0, v69, s[4:5]
	global_store_dword v[60:61], v63, off
	s_waitcnt lgkmcnt(1)
	v_mfma_f32_16x16x32_bf16 v[60:63], v[242:245], v[76:79], v[64:67]
	v_ashrrev_i32_e32 v69, 31, v68
	s_nop 1
	v_lshlrev_b64 v[64:65], 14, v[68:69]
	s_waitcnt lgkmcnt(0)
	v_mfma_f32_16x16x32_bf16 v[60:63], v[246:249], v[80:83], v[60:63]
	v_lshl_add_u64 v[64:65], v[182:183], 0, v[64:65]
	v_add_co_u32_e64 v66, s[4:5], s56, v64
	s_nop 1
	v_addc_co_u32_e64 v67, s[4:5], 0, v65, s[4:5]
	s_nop 2
	global_store_dword v[64:65], v60, off
	v_add_co_u32_e64 v60, s[4:5], s57, v64
	global_store_dword v[66:67], v61, off
	s_nop 0
	v_addc_co_u32_e64 v61, s[4:5], 0, v65, s[4:5]
	global_store_dword v[60:61], v62, off
	v_add_co_u32_e64 v60, s[4:5], s58, v64
	s_nop 1
	v_addc_co_u32_e64 v61, s[4:5], 0, v65, s[4:5]
	global_store_dword v[60:61], v63, off
	v_add_u32_e32 v100, v252, v212
	v_add_u32_e32 v218, v100, v217
	ds_read_b128 v[60:63], v100
	ds_read_b128 v[64:67], v100 offset:64
	ds_read_b128 v[68:71], v100 offset:128
	ds_read_b128 v[72:75], v100 offset:192
	v_add_u32_e32 v222, 0xd000, v218
	v_add_u32_e32 v100, 0x1000, v100
	ds_read_b128 v[218:221], v222
	ds_read_b128 v[222:225], v222 offset:64
	ds_read_b128 v[226:229], v100 offset:256
	ds_read_b128 v[230:233], v100 offset:320
	ds_read_b128 v[234:237], v100 offset:384
	ds_read_b128 v[238:241], v100 offset:448
	v_add_u32_e32 v100, 0xe000, v253
	ds_read_b128 v[242:245], v100 offset:512
	ds_read_b128 v[246:249], v100 offset:576
	s_waitcnt lgkmcnt(11)
	v_mfma_f32_16x16x32_bf16 v[60:63], v[60:63], v[84:87], 0
	s_waitcnt lgkmcnt(10)
	v_mfma_f32_16x16x32_bf16 v[60:63], v[64:67], v[88:91], v[60:63]
	v_add_u32_e32 v64, 32, v250
	v_ashrrev_i32_e32 v65, 31, v64
	v_lshlrev_b64 v[64:65], 14, v[64:65]
	s_waitcnt lgkmcnt(9)
	v_mfma_f32_16x16x32_bf16 v[60:63], v[68:71], v[92:95], v[60:63]
	v_lshl_add_u64 v[64:65], v[182:183], 0, v[64:65]
	v_cndmask_b32_e32 v69, v179, v65, vcc
	v_cndmask_b32_e32 v68, v178, v64, vcc
	s_waitcnt lgkmcnt(8)
	v_mfma_f32_16x16x32_bf16 v[60:63], v[72:75], v[96:99], v[60:63]
	v_add_co_u32_e64 v70, s[4:5], s56, v68
	s_waitcnt lgkmcnt(7)
	v_mfma_f32_16x16x32_bf16 v[60:63], v[218:221], v[76:79], v[60:63]
	v_addc_co_u32_e64 v71, s[4:5], 0, v69, s[4:5]
	s_waitcnt lgkmcnt(5)
	v_mfma_f32_16x16x32_bf16 v[64:67], v[226:229], v[84:87], 0
	v_mfma_f32_16x16x32_bf16 v[60:63], v[222:225], v[80:83], v[60:63]
	s_waitcnt lgkmcnt(4)
	v_mfma_f32_16x16x32_bf16 v[64:67], v[230:233], v[88:91], v[64:67]
	s_waitcnt lgkmcnt(3)
	v_mfma_f32_16x16x32_bf16 v[64:67], v[234:237], v[92:95], v[64:67]
	s_nop 3
	global_store_dword v[68:69], v60, off
	v_add_co_u32_e64 v60, s[4:5], s57, v68
	global_store_dword v[70:71], v61, off
	s_nop 0
	v_addc_co_u32_e64 v61, s[4:5], 0, v69, s[4:5]
	global_store_dword v[60:61], v62, off
	v_add_co_u32_e64 v60, s[4:5], s58, v68
	s_nop 1
	v_addc_co_u32_e64 v61, s[4:5], 0, v69, s[4:5]
	global_store_dword v[60:61], v63, off
	s_waitcnt lgkmcnt(2)
	v_mfma_f32_16x16x32_bf16 v[60:63], v[238:241], v[96:99], v[64:67]
	s_waitcnt lgkmcnt(1)
	v_mfma_f32_16x16x32_bf16 v[60:63], v[242:245], v[76:79], v[60:63]
	s_nop 0
	v_add_u32_e32 v64, 48, v250
	v_ashrrev_i32_e32 v65, 31, v64
	v_lshlrev_b64 v[64:65], 14, v[64:65]
	v_lshl_add_u64 v[64:65], v[182:183], 0, v[64:65]
	s_waitcnt lgkmcnt(0)
	v_mfma_f32_16x16x32_bf16 v[60:63], v[246:249], v[80:83], v[60:63]
	v_cndmask_b32_e32 v64, v180, v64, vcc
	v_cndmask_b32_e32 v65, v181, v65, vcc
	v_add_co_u32_e32 v66, vcc, s56, v64
	s_nop 1
	v_addc_co_u32_e32 v67, vcc, 0, v65, vcc
	s_nop 1
	global_store_dword v[64:65], v60, off
	v_add_co_u32_e32 v60, vcc, s57, v64
	global_store_dword v[66:67], v61, off
	s_nop 0
	v_addc_co_u32_e32 v61, vcc, 0, v65, vcc
	global_store_dword v[60:61], v62, off
	v_add_co_u32_e32 v60, vcc, s58, v64
	s_nop 1
	v_addc_co_u32_e32 v61, vcc, 0, v65, vcc
	global_store_dword v[60:61], v63, off
	v_lshl_add_u32 v100, v200, 2, s65
	v_add_u32_e32 v234, v100, v103
	v_add_u32_e32 v64, 0x8800, v234
	v_add_u32_e32 v88, 0x9000, v234
	v_add_u32_e32 v96, 0x9800, v234
	ds_read_b128 v[60:63], v64
	ds_read_b128 v[64:67], v64 offset:64
	ds_read_b128 v[68:71], v100 offset:62464
	ds_read_b128 v[72:75], v100 offset:62528
	ds_read_b128 v[84:87], v88 offset:256
	ds_read_b128 v[88:91], v88 offset:320
	ds_read_b128 v[92:95], v96 offset:512
	ds_read_b128 v[96:99], v96 offset:576
	ds_read_b128 v[218:221], v100 offset:62592
	ds_read_b128 v[222:225], v100 offset:62656
	v_add_u32_e32 v230, 0xa000, v234
	ds_read_b128 v[226:229], v230 offset:768
	ds_read_b128 v[230:233], v230 offset:832
	s_waitcnt lgkmcnt(9)
	v_pk_mul_f32 v[2:3], v[2:3], v[70:71]
	v_pk_mul_f32 v[0:1], v[0:1], v[68:69]
	s_waitcnt lgkmcnt(8)
	v_pk_mul_f32 v[6:7], v[6:7], v[74:75]
	v_pk_mul_f32 v[4:5], v[4:5], v[72:73]
	s_waitcnt lgkmcnt(3)
	v_pk_mul_f32 v[10:11], v[10:11], v[220:221]
	v_pk_mul_f32 v[8:9], v[8:9], v[218:219]
	s_waitcnt lgkmcnt(2)
	v_pk_mul_f32 v[14:15], v[14:15], v[224:225]
	v_pk_mul_f32 v[12:13], v[12:13], v[222:223]
	v_mfma_f32_16x16x32_bf16 v[0:3], v[60:63], v[76:79], v[0:3]
	v_mfma_f32_16x16x32_bf16 v[4:7], v[84:87], v[76:79], v[4:7]
	v_mfma_f32_16x16x32_bf16 v[8:11], v[92:95], v[76:79], v[8:11]
	s_waitcnt lgkmcnt(1)
	v_mfma_f32_16x16x32_bf16 v[12:15], v[226:229], v[76:79], v[12:15]
	v_mfma_f32_16x16x32_bf16 v[0:3], v[64:67], v[80:83], v[0:3]
	v_mfma_f32_16x16x32_bf16 v[4:7], v[88:91], v[80:83], v[4:7]
	v_mfma_f32_16x16x32_bf16 v[8:11], v[96:99], v[80:83], v[8:11]
	s_waitcnt lgkmcnt(0)
	v_mfma_f32_16x16x32_bf16 v[12:15], v[230:233], v[80:83], v[12:15]
	v_add_u32_e32 v64, 0xa800, v234
	v_add_u32_e32 v88, 0xb000, v234
	v_add_u32_e32 v96, 0xb800, v234
	ds_read_b128 v[60:63], v64 offset:1024
	ds_read_b128 v[64:67], v64 offset:1088
	ds_read_b128 v[68:71], v100 offset:62720
	ds_read_b128 v[72:75], v100 offset:62784
	ds_read_b128 v[84:87], v88 offset:1280
	ds_read_b128 v[88:91], v88 offset:1344
	ds_read_b128 v[92:95], v96 offset:1536
	ds_read_b128 v[96:99], v96 offset:1600
	ds_read_b128 v[218:221], v100 offset:62848
	ds_read_b128 v[222:225], v100 offset:62912
	v_add_u32_e32 v100, 0xc000, v234
	ds_read_b128 v[226:229], v100 offset:1792
	ds_read_b128 v[230:233], v100 offset:1856
	s_waitcnt lgkmcnt(9)
	v_pk_mul_f32 v[18:19], v[18:19], v[70:71]
	v_pk_mul_f32 v[16:17], v[16:17], v[68:69]
	s_waitcnt lgkmcnt(8)
	v_pk_mul_f32 v[22:23], v[22:23], v[74:75]
	v_pk_mul_f32 v[20:21], v[20:21], v[72:73]
	s_waitcnt lgkmcnt(3)
	v_pk_mul_f32 v[26:27], v[26:27], v[220:221]
	v_pk_mul_f32 v[24:25], v[24:25], v[218:219]
	s_waitcnt lgkmcnt(2)
	v_pk_mul_f32 v[30:31], v[30:31], v[224:225]
	v_pk_mul_f32 v[28:29], v[28:29], v[222:223]
	v_mfma_f32_16x16x32_bf16 v[16:19], v[60:63], v[76:79], v[16:19]
	v_mfma_f32_16x16x32_bf16 v[20:23], v[84:87], v[76:79], v[20:23]
	v_mfma_f32_16x16x32_bf16 v[24:27], v[92:95], v[76:79], v[24:27]
	s_waitcnt lgkmcnt(1)
	v_mfma_f32_16x16x32_bf16 v[28:31], v[226:229], v[76:79], v[28:31]
	v_mfma_f32_16x16x32_bf16 v[16:19], v[64:67], v[80:83], v[16:19]
	v_mfma_f32_16x16x32_bf16 v[20:23], v[88:91], v[80:83], v[20:23]
	v_mfma_f32_16x16x32_bf16 v[24:27], v[96:99], v[80:83], v[24:27]
	s_waitcnt lgkmcnt(0)
	v_mfma_f32_16x16x32_bf16 v[28:31], v[230:233], v[80:83], v[28:31]
	s_add_i32 s64, s64, 16
	s_add_i32 s22, s22, 28
	v_add_u32_e32 v142, 32, v142
	s_cmp_lg_u32 s62, s61
	v_add_u32_e32 v211, 64, v211
	s_cbranch_scc0 .LBB0_945
	s_waitcnt vmcnt(16)
	v_lshlrev_b32_e32 v184, 16, v184
	v_lshlrev_b32_e32 v185, 16, v185
	v_lshlrev_b32_e32 v186, 16, v186
	v_lshlrev_b32_e32 v187, 16, v187
	v_lshlrev_b32_e32 v188, 16, v188
	v_lshlrev_b32_e32 v189, 16, v189
	v_lshlrev_b32_e32 v190, 16, v190
	v_lshlrev_b32_e32 v191, 16, v191
	v_lshlrev_b32_e32 v192, 16, v192
	v_lshlrev_b32_e32 v193, 16, v193
	v_lshlrev_b32_e32 v194, 16, v194
	v_lshlrev_b32_e32 v195, 16, v195
	v_lshlrev_b32_e32 v196, 16, v196
	v_lshlrev_b32_e32 v197, 16, v197
	v_lshlrev_b32_e32 v198, 16, v198
	v_lshlrev_b32_e32 v199, 16, v199
	s_andn2_b64 vcc, exec, s[40:41]
	s_cbranch_vccnz .Lm2_nomask_a
	v_cmp_gt_u32_e32 vcc, s67, v164
	s_nop 1
	v_cndmask_b32_e32 v188, 0, v188, vcc
	v_cmp_gt_u32_e32 vcc, s67, v165
	s_nop 1
	v_cndmask_b32_e32 v189, 0, v189, vcc
	v_cmp_gt_u32_e32 vcc, s67, v106
	s_nop 1
	v_cndmask_b32_e32 v190, 0, v190, vcc
	v_cmp_gt_u32_e32 vcc, s67, v107
	s_nop 1
	v_cndmask_b32_e32 v191, 0, v191, vcc
	v_cmp_gt_u32_e32 vcc, s67, v162
	s_nop 1
	v_cndmask_b32_e32 v196, 0, v196, vcc
	v_cmp_gt_u32_e32 vcc, s67, v163
	s_nop 1
	v_cndmask_b32_e32 v197, 0, v197, vcc
	v_cmp_gt_u32_e32 vcc, s67, v110
	s_nop 1
	v_cndmask_b32_e32 v198, 0, v198, vcc
	v_cmp_gt_u32_e32 vcc, s67, v111
	s_nop 1
	v_cndmask_b32_e32 v199, 0, v199, vcc
.Lm2_nomask_a:
	v_mov_b64_e32 v[72:73], v[192:193]
	v_mov_b64_e32 v[74:75], v[194:195]
	v_mov_b64_e32 v[68:69], v[184:185]
	v_mov_b64_e32 v[70:71], v[186:187]
	v_mov_b64_e32 v[64:65], v[196:197]
	v_mov_b64_e32 v[66:67], v[198:199]
	v_mov_b64_e32 v[60:61], v[188:189]
	v_mov_b64_e32 v[62:63], v[190:191]
	s_branch .LBB0_1032

.LBB0_2604:
	s_bitcmp1_b32 s50, 0
	s_cselect_b32 s4, 0xf600, 0
	s_add_i32 s63, s4, 0
	v_and_b32_e32 v80, 3, v201
	v_lshlrev_b32_e32 v80, 3, v80
	v_mov_b32_e32 v81, 0xf8e81000
	v_lshrrev_b32_e32 v80, v80, v81
	v_bfe_i32 v80, v80, 0, 8
	v_lshl_add_u32 v77, v208, 1, s63
	v_lshl_add_u32 v78, v209, 1, s63
	v_lshl_add_u32 v76, v140, 1, v77
	v_add_u32_e32 v76, v76, v80
	v_add_u32_e32 v84, 0x4400, v76
	v_lshl_add_u32 v79, v109, 1, v78
	v_add_u32_e32 v79, v79, v80
	v_add_u32_e32 v82, 0x8800, v79
	s_mov_b64 s[4:5], -1
	s_and_b64 vcc, exec, s[42:43]
	v_lshl_add_u32 v77, v215, 1, v77
	v_add_u32_e32 v77, v77, v80
	v_add_u32_e32 v85, 0x4400, v77
	v_lshl_add_u32 v78, v216, 1, v78
	v_add_u32_e32 v78, v78, v80
	v_add_u32_e32 v83, 0x8800, v78
	s_waitcnt vmcnt(21)
	ds_write2_b64 v76, v[32:33], v[34:35] offset1:2
	s_waitcnt vmcnt(20)
	ds_write2_b64 v82, v[36:37], v[38:39] offset1:2
	s_cbranch_vccz .LBB0_2606
	s_waitcnt vmcnt(19)
	ds_write2_b64 v77, v[40:41], v[42:43] offset1:2
	s_waitcnt vmcnt(18)
	ds_write2_b64 v83, v[44:45], v[46:47] offset1:2
	s_mov_b64 s[4:5], 0

.LBB0_2608:
	v_lshlrev_b32_e32 v76, 1, v109
	v_add3_u32 v76, s63, v76, v114
	v_add_u32_e32 v76, v76, v80
	v_add_u32_e32 v76, 0xd000, v76
	s_waitcnt vmcnt(17)
	ds_write2_b64 v76, v[48:49], v[50:51] offset1:2
	s_and_saveexec_b64 s[4:5], s[0:1]
	s_cbranch_execz .LBB0_2610
	v_lshl_add_u32 v76, v201, 2, s63
	s_waitcnt vmcnt(16)
	ds_write_b32 v76, v210 offset:62464

.LBB0_2615:
	s_ashr_i32 s49, s48, 31
	s_lshl_b64 s[68:69], s[48:49], 14
	s_lshl_b64 s[66:67], s[48:49], 13
	v_lshl_add_u64 v[40:41], v[166:167], 0, s[68:69]
	v_lshl_add_u64 v[42:43], v[172:173], 0, s[68:69]
	v_lshl_add_u64 v[32:33], v[116:117], 1, v[40:41]
	v_lshl_add_u64 v[36:37], v[118:119], 1, v[42:43]
	v_lshl_add_u64 v[40:41], v[120:121], 1, v[40:41]
	v_lshl_add_u64 v[44:45], v[122:123], 1, v[42:43]
	v_lshl_add_u64 v[48:49], v[174:175], 0, s[66:67]
	s_lshl_b64 s[48:49], s[48:49], 9
	global_load_dwordx4 v[32:35], v[32:33], off
	s_nop 0
	global_load_dwordx4 v[36:39], v[36:37], off
	s_nop 0
	global_load_dwordx4 v[40:43], v[40:41], off
	s_nop 0
	global_load_dwordx4 v[44:47], v[44:45], off
	v_lshl_add_u64 v[76:77], v[176:177], 0, s[48:49]
	global_load_dwordx4 v[48:51], v[48:49], off
	s_nop 0
	global_load_dword v210, v[76:77], off
	s_mov_b64 s[48:49], -1
	s_and_b64 vcc, exec, s[42:43]
	s_cbranch_vccz .LBB0_2617
	s_and_b64 s[48:49], s[4:5], exec
	v_add_u32_e32 v76, 64, v211
	s_cselect_b32 s45, 64, 32
	v_cndmask_b32_e64 v92, v126, v76, s[4:5]
	s_add_i32 s4, s45, -1
	v_min_i32_e32 v76, s4, v200
	v_add_u32_e32 v78, v76, v92
	v_lshrrev_b32_e32 v76, 8, v78
	v_lshlrev_b32_e32 v78, 9, v78
	v_mul_i32_i24_e32 v76, 60, v76
	v_and_b32_e32 v100, 0x1fe00, v78
	v_min_i32_e32 v78, s4, v105
	v_ashrrev_i32_e32 v77, 31, v76
	v_add_u32_e32 v80, v78, v92
	v_lshlrev_b64 v[76:77], 17, v[76:77]
	v_lshrrev_b32_e32 v78, 8, v80
	v_lshl_add_u64 v[76:77], s[10:11], 0, v[76:77]
	v_mul_i32_i24_e32 v78, 60, v78
	v_lshlrev_b32_e32 v80, 9, v80
	v_lshl_add_u64 v[76:77], v[76:77], 0, v[100:101]
	v_ashrrev_i32_e32 v79, 31, v78
	v_and_b32_e32 v100, 0x1fe00, v80
	v_min_i32_e32 v80, s4, v202
	v_lshlrev_b64 v[78:79], 17, v[78:79]
	v_add_u32_e32 v82, v80, v92
	v_lshl_add_u64 v[78:79], s[10:11], 0, v[78:79]
	v_lshrrev_b32_e32 v80, 8, v82
	v_lshlrev_b32_e32 v82, 9, v82
	v_lshl_add_u64 v[78:79], v[78:79], 0, v[100:101]
	v_mul_i32_i24_e32 v80, 60, v80
	v_and_b32_e32 v100, 0x1fe00, v82
	v_min_i32_e32 v82, s4, v203
	v_ashrrev_i32_e32 v81, 31, v80
	v_add_u32_e32 v84, v82, v92
	v_lshlrev_b64 v[80:81], 17, v[80:81]
	v_lshrrev_b32_e32 v82, 8, v84
	v_lshl_add_u64 v[80:81], s[10:11], 0, v[80:81]
	v_mul_i32_i24_e32 v82, 60, v82
	v_lshlrev_b32_e32 v84, 9, v84
	v_lshl_add_u64 v[80:81], v[80:81], 0, v[100:101]
	v_ashrrev_i32_e32 v83, 31, v82
	v_and_b32_e32 v100, 0x1fe00, v84
	v_min_i32_e32 v84, s4, v204
	v_lshlrev_b64 v[82:83], 17, v[82:83]
	v_add_u32_e32 v86, v84, v92
	v_lshl_add_u64 v[82:83], s[10:11], 0, v[82:83]
	v_lshrrev_b32_e32 v84, 8, v86
	v_lshlrev_b32_e32 v86, 9, v86
	v_lshl_add_u64 v[82:83], v[82:83], 0, v[100:101]
	v_mul_i32_i24_e32 v84, 60, v84
	v_and_b32_e32 v100, 0x1fe00, v86
	v_min_i32_e32 v86, s4, v205
	v_ashrrev_i32_e32 v85, 31, v84
	v_add_u32_e32 v88, v86, v92
	v_lshlrev_b64 v[84:85], 17, v[84:85]
	v_lshrrev_b32_e32 v86, 8, v88
	v_lshl_add_u64 v[84:85], s[10:11], 0, v[84:85]
	v_mul_i32_i24_e32 v86, 60, v86
	v_lshlrev_b32_e32 v88, 9, v88
	v_lshl_add_u64 v[84:85], v[84:85], 0, v[100:101]
	v_ashrrev_i32_e32 v87, 31, v86
	v_and_b32_e32 v100, 0x1fe00, v88
	v_min_i32_e32 v88, s4, v206
	v_lshlrev_b64 v[86:87], 17, v[86:87]
	v_add_u32_e32 v90, v88, v92
	v_lshl_add_u64 v[86:87], s[10:11], 0, v[86:87]
	v_lshrrev_b32_e32 v88, 8, v90
	v_lshlrev_b32_e32 v90, 9, v90
	v_lshl_add_u64 v[86:87], v[86:87], 0, v[100:101]
	v_and_b32_e32 v100, 0x1fe00, v90
	v_min_i32_e32 v90, s4, v207
	v_add_u32_e32 v93, v90, v92
	v_mul_i32_i24_e32 v88, 60, v88
	v_lshrrev_b32_e32 v90, 8, v93
	v_ashrrev_i32_e32 v89, 31, v88
	v_mul_i32_i24_e32 v90, 60, v90
	v_lshlrev_b64 v[88:89], 17, v[88:89]
	v_ashrrev_i32_e32 v91, 31, v90
	v_lshl_add_u64 v[88:89], s[10:11], 0, v[88:89]
	v_lshlrev_b64 v[90:91], 17, v[90:91]
	v_lshlrev_b32_e32 v93, 9, v93
	v_lshl_add_u64 v[88:89], v[88:89], 0, v[100:101]
	v_lshl_add_u64 v[90:91], s[10:11], 0, v[90:91]
	v_and_b32_e32 v100, 0x1fe00, v93
	v_lshl_add_u64 v[90:91], v[90:91], 0, v[100:101]
	v_lshl_add_u64 v[76:77], v[76:77], 0, v[124:125]
	v_lshl_add_u64 v[90:91], v[90:91], 0, v[124:125]
	v_lshl_add_u64 v[76:77], v[76:77], 0, v[170:171]
	v_lshl_add_u64 v[78:79], v[78:79], 0, v[124:125]
	v_lshl_add_u64 v[80:81], v[80:81], 0, v[124:125]
	v_lshl_add_u64 v[82:83], v[82:83], 0, v[124:125]
	v_lshl_add_u64 v[84:85], v[84:85], 0, v[124:125]
	v_lshl_add_u64 v[86:87], v[86:87], 0, v[124:125]
	v_lshl_add_u64 v[88:89], v[88:89], 0, v[124:125]
	v_lshl_add_u64 v[90:91], v[90:91], 0, v[170:171]
	v_lshl_add_u64 v[78:79], v[78:79], 0, v[170:171]
	v_lshl_add_u64 v[80:81], v[80:81], 0, v[170:171]
	v_lshl_add_u64 v[82:83], v[82:83], 0, v[170:171]
	v_lshl_add_u64 v[84:85], v[84:85], 0, v[170:171]
	v_lshl_add_u64 v[86:87], v[86:87], 0, v[170:171]
	v_lshl_add_u64 v[88:89], v[88:89], 0, v[170:171]
	global_load_ushort v184, v[76:77], off
	global_load_ushort v185, v[78:79], off
	global_load_ushort v186, v[80:81], off
	global_load_ushort v187, v[82:83], off
	global_load_ushort v192, v[84:85], off
	global_load_ushort v193, v[86:87], off
	global_load_ushort v194, v[88:89], off
	s_nop 0
	global_load_ushort v195, v[90:91], off
	v_min_i32_e32 v76, s4, v108
	v_add_u32_e32 v78, v76, v92
	v_lshrrev_b32_e32 v76, 8, v78
	v_mul_i32_i24_e32 v76, 60, v76
	v_lshlrev_b32_e32 v78, 9, v78
	v_ashrrev_i32_e32 v77, 31, v76
	v_and_b32_e32 v100, 0x1fe00, v78
	v_min_i32_e32 v78, s4, v127
	v_lshlrev_b64 v[76:77], 17, v[76:77]
	v_add_u32_e32 v80, v78, v92
	v_lshl_add_u64 v[76:77], s[10:11], 0, v[76:77]
	v_lshrrev_b32_e32 v78, 8, v80
	v_lshlrev_b32_e32 v80, 9, v80
	v_lshl_add_u64 v[76:77], v[76:77], 0, v[100:101]
	v_mul_i32_i24_e32 v78, 60, v78
	v_and_b32_e32 v100, 0x1fe00, v80
	v_min_i32_e32 v80, s4, v106
	v_ashrrev_i32_e32 v79, 31, v78
	v_add_u32_e32 v82, v80, v92
	v_lshlrev_b64 v[78:79], 17, v[78:79]
	v_lshrrev_b32_e32 v80, 8, v82
	v_lshl_add_u64 v[78:79], s[10:11], 0, v[78:79]
	v_mul_i32_i24_e32 v80, 60, v80
	v_lshlrev_b32_e32 v82, 9, v82
	v_lshl_add_u64 v[78:79], v[78:79], 0, v[100:101]
	v_ashrrev_i32_e32 v81, 31, v80
	v_and_b32_e32 v100, 0x1fe00, v82
	v_min_i32_e32 v82, s4, v107
	v_lshlrev_b64 v[80:81], 17, v[80:81]
	v_add_u32_e32 v84, v82, v92
	v_lshl_add_u64 v[80:81], s[10:11], 0, v[80:81]
	v_lshrrev_b32_e32 v82, 8, v84
	v_lshlrev_b32_e32 v84, 9, v84
	v_lshl_add_u64 v[80:81], v[80:81], 0, v[100:101]
	v_mul_i32_i24_e32 v82, 60, v82
	v_and_b32_e32 v100, 0x1fe00, v84
	v_min_i32_e32 v84, s4, v112
	v_ashrrev_i32_e32 v83, 31, v82
	v_add_u32_e32 v86, v84, v92
	v_lshlrev_b64 v[82:83], 17, v[82:83]
	v_lshrrev_b32_e32 v84, 8, v86
	v_lshl_add_u64 v[82:83], s[10:11], 0, v[82:83]
	v_mul_i32_i24_e32 v84, 60, v84
	v_lshlrev_b32_e32 v86, 9, v86
	v_lshl_add_u64 v[82:83], v[82:83], 0, v[100:101]
	v_ashrrev_i32_e32 v85, 31, v84
	v_and_b32_e32 v100, 0x1fe00, v86
	v_min_i32_e32 v86, s4, v141
	v_lshlrev_b64 v[84:85], 17, v[84:85]
	v_add_u32_e32 v88, v86, v92
	v_lshl_add_u64 v[84:85], s[10:11], 0, v[84:85]
	v_lshrrev_b32_e32 v86, 8, v88
	v_lshlrev_b32_e32 v88, 9, v88
	v_lshl_add_u64 v[84:85], v[84:85], 0, v[100:101]
	v_and_b32_e32 v100, 0x1fe00, v88
	v_min_i32_e32 v88, s4, v110
	v_add_u32_e32 v91, v88, v92
	v_mul_i32_i24_e32 v86, 60, v86
	v_lshrrev_b32_e32 v88, 8, v91
	v_ashrrev_i32_e32 v87, 31, v86
	v_mul_i32_i24_e32 v88, 60, v88
	v_lshlrev_b64 v[86:87], 17, v[86:87]
	v_ashrrev_i32_e32 v89, 31, v88
	v_lshl_add_u64 v[86:87], s[10:11], 0, v[86:87]
	v_lshlrev_b64 v[88:89], 17, v[88:89]
	v_lshlrev_b32_e32 v91, 9, v91
	v_lshl_add_u64 v[86:87], v[86:87], 0, v[100:101]
	v_lshl_add_u64 v[88:89], s[10:11], 0, v[88:89]
	v_and_b32_e32 v100, 0x1fe00, v91
	v_lshl_add_u64 v[88:89], v[88:89], 0, v[100:101]
	v_lshl_add_u64 v[76:77], v[76:77], 0, v[124:125]
	v_lshl_add_u64 v[78:79], v[78:79], 0, v[124:125]
	v_lshl_add_u64 v[80:81], v[80:81], 0, v[124:125]
	v_lshl_add_u64 v[84:85], v[84:85], 0, v[124:125]
	v_lshl_add_u64 v[88:89], v[88:89], 0, v[124:125]
	v_lshl_add_u64 v[76:77], v[76:77], 0, v[170:171]
	v_lshl_add_u64 v[78:79], v[78:79], 0, v[170:171]
	v_lshl_add_u64 v[80:81], v[80:81], 0, v[170:171]
	v_lshl_add_u64 v[84:85], v[84:85], 0, v[170:171]
	v_lshl_add_u64 v[88:89], v[88:89], 0, v[170:171]
	global_load_ushort v189, v[78:79], off
	s_nop 0
	global_load_ushort v198, v[88:89], off
	s_nop 0
	global_load_ushort v196, v[84:85], off
	s_nop 0
	global_load_ushort v190, v[80:81], off
	s_nop 0
	global_load_ushort v188, v[76:77], off
	v_lshl_add_u64 v[76:77], v[82:83], 0, v[124:125]
	v_lshl_add_u64 v[78:79], v[86:87], 0, v[124:125]
	v_lshl_add_u64 v[76:77], v[76:77], 0, v[170:171]
	v_lshl_add_u64 v[78:79], v[78:79], 0, v[170:171]
	global_load_ushort v191, v[76:77], off
	s_nop 0
	global_load_ushort v197, v[78:79], off
	v_min_i32_e32 v76, s4, v111
	v_add_u32_e32 v79, v76, v92
	v_lshrrev_b32_e32 v76, 8, v79
	v_mul_i32_i24_e32 v76, 60, v76
	v_ashrrev_i32_e32 v77, 31, v76
	v_lshlrev_b64 v[76:77], 17, v[76:77]
	v_lshlrev_b32_e32 v79, 9, v79
	v_lshl_add_u64 v[76:77], s[10:11], 0, v[76:77]
	v_and_b32_e32 v100, 0x1fe00, v79
	v_lshl_add_u64 v[76:77], v[76:77], 0, v[100:101]
	v_lshl_add_u64 v[76:77], v[76:77], 0, v[124:125]
	v_lshl_add_u64 v[76:77], v[76:77], 0, v[170:171]
	global_load_ushort v199, v[76:77], off
	s_mov_b64 s[48:49], 0
.LBB0_2617:
	s_andn2_b64 vcc, exec, s[48:49]
	s_cbranch_vccnz .LBB0_2620
	s_ashr_i32 s45, s44, 31
	s_lshl_b64 s[4:5], s[44:45], 14
	v_lshl_add_u64 v[52:53], v[168:169], 0, s[4:5]
	s_add_u32 s4, s54, s4
	s_addc_u32 s5, s55, s5
	v_lshl_add_u64 v[54:55], v[116:117], 1, v[52:53]
	s_waitcnt vmcnt(22)
	v_lshl_add_u64 v[56:57], v[120:121], 1, v[52:53]
	v_lshl_add_u64 v[52:53], v[136:137], 1, s[4:5]
	v_lshl_add_u64 v[58:59], v[150:151], 1, s[4:5]
	v_lshl_add_u64 v[76:77], v[152:153], 1, s[4:5]
	v_lshl_add_u64 v[78:79], v[154:155], 1, s[4:5]
	v_lshl_add_u64 v[80:81], v[142:143], 1, s[4:5]
	v_lshl_add_u64 v[82:83], v[156:157], 1, s[4:5]
	v_lshl_add_u64 v[84:85], v[158:159], 1, s[4:5]
	v_lshl_add_u64 v[86:87], v[160:161], 1, s[4:5]
	global_load_ushort v184, v[52:53], off
	global_load_ushort v185, v[58:59], off
	global_load_ushort v186, v[76:77], off
	global_load_ushort v187, v[78:79], off
	global_load_ushort v192, v[80:81], off
	global_load_ushort v193, v[82:83], off
	global_load_ushort v194, v[84:85], off
	global_load_ushort v195, v[86:87], off
	v_lshl_add_u64 v[52:53], v[128:129], 1, s[4:5]
	v_lshl_add_u64 v[58:59], v[130:131], 1, s[4:5]
	v_lshl_add_u64 v[76:77], v[132:133], 1, s[4:5]
	v_lshl_add_u64 v[78:79], v[134:135], 1, s[4:5]
	v_lshl_add_u64 v[80:81], v[138:139], 1, s[4:5]
	v_lshl_add_u64 v[82:83], v[148:149], 1, s[4:5]
	v_lshl_add_u64 v[84:85], v[144:145], 1, s[4:5]
	v_lshl_add_u64 v[86:87], v[146:147], 1, s[4:5]
	global_load_ushort v188, v[52:53], off
	global_load_ushort v189, v[58:59], off
	s_nop 0
	global_load_ushort v190, v[76:77], off
	s_nop 0
	global_load_ushort v191, v[78:79], off
	s_nop 0
	global_load_ushort v196, v[80:81], off
	global_load_ushort v197, v[82:83], off
	s_nop 0
	global_load_ushort v198, v[84:85], off
	global_load_ushort v199, v[86:87], off
	s_nop 0
	global_load_dwordx4 v[52:55], v[54:55], off
	s_nop 0
	global_load_dwordx4 v[56:59], v[56:57], off
	s_branch .LBB0_2620

.LBB0_2622:
.LBB0_2623:
	v_lshlrev_b32_e32 v76, 2, v200
	v_lshlrev_b32_e32 v77, 1, v113
	v_add3_u32 v100, s63, v76, v77
	v_add_u32_e32 v222, 0x4000, v100
	v_add_u32_e32 v238, 0x5000, v100
	ds_read_b128 v[76:79], v222 offset:1024
	ds_read_b128 v[80:83], v222 offset:1088
	ds_read_b128 v[218:221], v222 offset:1152
	ds_read_b128 v[222:225], v222 offset:1216
	ds_read_b128 v[226:229], v238 offset:1280
	ds_read_b128 v[230:233], v238 offset:1344
	ds_read_b128 v[234:237], v238 offset:1408
	ds_read_b128 v[238:241], v238 offset:1472
	s_waitcnt lgkmcnt(7)
	v_mfma_f32_16x16x32_bf16 v[68:71], v[76:79], v[84:87], v[68:71]
	s_waitcnt lgkmcnt(3)
	v_mfma_f32_16x16x32_bf16 v[72:75], v[226:229], v[84:87], v[72:75]
	v_mfma_f32_16x16x32_bf16 v[68:71], v[80:83], v[88:91], v[68:71]
	s_waitcnt lgkmcnt(2)
	v_mfma_f32_16x16x32_bf16 v[72:75], v[230:233], v[88:91], v[72:75]
	v_mfma_f32_16x16x32_bf16 v[68:71], v[218:221], v[92:95], v[68:71]
	s_waitcnt lgkmcnt(1)
	v_mfma_f32_16x16x32_bf16 v[72:75], v[234:237], v[92:95], v[72:75]
	v_mfma_f32_16x16x32_bf16 v[68:71], v[222:225], v[96:99], v[68:71]
	s_waitcnt lgkmcnt(0)
	v_mfma_f32_16x16x32_bf16 v[72:75], v[238:241], v[96:99], v[72:75]
	v_add_u32_e32 v222, 0x6000, v100
	v_add_u32_e32 v100, 0x7000, v100
	ds_read_b128 v[76:79], v222 offset:1536
	ds_read_b128 v[80:83], v222 offset:1600
	ds_read_b128 v[218:221], v222 offset:1664
	ds_read_b128 v[222:225], v222 offset:1728
	ds_read_b128 v[226:229], v100 offset:1792
	ds_read_b128 v[230:233], v100 offset:1856
	ds_read_b128 v[234:237], v100 offset:1920
	ds_read_b128 v[238:241], v100 offset:1984
	s_waitcnt lgkmcnt(7)
	v_mfma_f32_16x16x32_bf16 v[60:63], v[76:79], v[84:87], v[60:63]
	s_waitcnt lgkmcnt(3)
	v_mfma_f32_16x16x32_bf16 v[64:67], v[226:229], v[84:87], v[64:67]
	v_mfma_f32_16x16x32_bf16 v[60:63], v[80:83], v[88:91], v[60:63]
	s_waitcnt lgkmcnt(2)
	v_mfma_f32_16x16x32_bf16 v[64:67], v[230:233], v[88:91], v[64:67]
	v_mfma_f32_16x16x32_bf16 v[60:63], v[218:221], v[92:95], v[60:63]
	s_waitcnt lgkmcnt(1)
	v_mfma_f32_16x16x32_bf16 v[64:67], v[234:237], v[92:95], v[64:67]
	v_mfma_f32_16x16x32_bf16 v[60:63], v[222:225], v[96:99], v[60:63]
	s_waitcnt lgkmcnt(0)
	v_mfma_f32_16x16x32_bf16 v[64:67], v[238:241], v[96:99], v[64:67]
	v_cvt_pk_bf16_f32 v76, v68, v69
	v_cvt_pk_bf16_f32 v77, v70, v71
	v_cvt_pk_bf16_f32 v78, v72, v73
	v_cvt_pk_bf16_f32 v79, v74, v75
	v_cvt_pk_bf16_f32 v80, v60, v61
	v_cvt_pk_bf16_f32 v81, v62, v63
	v_cvt_pk_bf16_f32 v82, v64, v65
	v_cvt_pk_bf16_f32 v83, v66, v67
.LBB0_2624:
	v_lshl_add_u32 v252, v200, 2, s63
	v_lshl_add_u32 v226, v113, 1, v252
	v_add_u32_e32 v218, v226, v213
	v_add_u32_e32 v222, 0xd000, v218
	v_add_u32_e32 v238, 0x1000, v226
	s_nop 0
	ds_read_b128 v[60:63], v226
	s_nop 0
	ds_read_b128 v[64:67], v226 offset:64
	ds_read_b128 v[68:71], v226 offset:128
	ds_read_b128 v[72:75], v226 offset:192
	ds_read_b128 v[218:221], v222
	ds_read_b128 v[222:225], v222 offset:64
	ds_read_b128 v[226:229], v238 offset:256
	ds_read_b128 v[230:233], v238 offset:320
	ds_read_b128 v[234:237], v238 offset:384
	ds_read_b128 v[238:241], v238 offset:448
	v_add_u32_e32 v253, v252, v115
	v_add_u32_e32 v246, 0xd000, v253
	ds_read_b128 v[242:245], v246
	ds_read_b128 v[246:249], v246 offset:64
	s_cmpk_lt_i32 s64, 0x80
	v_subrev_u32_e32 v100, 32, v126
	s_cselect_b64 vcc, -1, 0
	v_cndmask_b32_e32 v100, v100, v211, vcc
	v_or_b32_e32 v250, v100, v200
	s_waitcnt lgkmcnt(11)
	v_mfma_f32_16x16x32_bf16 v[60:63], v[60:63], v[84:87], 0
	v_ashrrev_i32_e32 v251, 31, v250
	s_waitcnt lgkmcnt(10)
	v_mfma_f32_16x16x32_bf16 v[60:63], v[64:67], v[88:91], v[60:63]
	v_lshlrev_b64 v[64:65], 14, v[250:251]
	s_waitcnt lgkmcnt(9)
	v_mfma_f32_16x16x32_bf16 v[60:63], v[68:71], v[92:95], v[60:63]
	v_lshl_add_u64 v[68:69], v[182:183], 0, v[64:65]
	v_add_co_u32_e64 v70, s[4:5], s58, v68
	s_waitcnt lgkmcnt(5)
	v_mfma_f32_16x16x32_bf16 v[226:229], v[226:229], v[84:87], 0
	v_addc_co_u32_e64 v71, s[4:5], 0, v69, s[4:5]
	v_mfma_f32_16x16x32_bf16 v[60:63], v[72:75], v[96:99], v[60:63]
	v_mfma_f32_16x16x32_bf16 v[60:63], v[218:221], v[76:79], v[60:63]
	s_waitcnt lgkmcnt(4)
	v_mfma_f32_16x16x32_bf16 v[64:67], v[230:233], v[88:91], v[226:229]
	v_mfma_f32_16x16x32_bf16 v[60:63], v[222:225], v[80:83], v[60:63]
	s_waitcnt lgkmcnt(3)
	v_mfma_f32_16x16x32_bf16 v[64:67], v[234:237], v[92:95], v[64:67]
	s_waitcnt lgkmcnt(2)
	v_mfma_f32_16x16x32_bf16 v[64:67], v[238:241], v[96:99], v[64:67]
	s_nop 3
	global_store_dword v[68:69], v60, off
	v_add_co_u32_e64 v60, s[4:5], s59, v68
	global_store_dword v[70:71], v61, off
	s_nop 0
	v_addc_co_u32_e64 v61, s[4:5], 0, v69, s[4:5]
	global_store_dword v[60:61], v62, off
	v_add_co_u32_e64 v60, s[4:5], s60, v68
	v_or_b32_e32 v68, 16, v250
	s_nop 0
	v_addc_co_u32_e64 v61, s[4:5], 0, v69, s[4:5]
	global_store_dword v[60:61], v63, off
	s_waitcnt lgkmcnt(1)
	v_mfma_f32_16x16x32_bf16 v[60:63], v[242:245], v[76:79], v[64:67]
	v_ashrrev_i32_e32 v69, 31, v68
	s_nop 1
	v_lshlrev_b64 v[64:65], 14, v[68:69]
	s_waitcnt lgkmcnt(0)
	v_mfma_f32_16x16x32_bf16 v[60:63], v[246:249], v[80:83], v[60:63]
	v_lshl_add_u64 v[64:65], v[182:183], 0, v[64:65]
	v_add_co_u32_e64 v66, s[4:5], s58, v64
	s_nop 1
	v_addc_co_u32_e64 v67, s[4:5], 0, v65, s[4:5]
	s_nop 2
	global_store_dword v[64:65], v60, off
	v_add_co_u32_e64 v60, s[4:5], s59, v64
	global_store_dword v[66:67], v61, off
	s_nop 0
	v_addc_co_u32_e64 v61, s[4:5], 0, v65, s[4:5]
	global_store_dword v[60:61], v62, off
	v_add_co_u32_e64 v60, s[4:5], s60, v64
	s_nop 1
	v_addc_co_u32_e64 v61, s[4:5], 0, v65, s[4:5]
	global_store_dword v[60:61], v63, off
	v_add_u32_e32 v100, v252, v212
	v_add_u32_e32 v218, v100, v217
	ds_read_b128 v[60:63], v100
	ds_read_b128 v[64:67], v100 offset:64
	ds_read_b128 v[68:71], v100 offset:128
	ds_read_b128 v[72:75], v100 offset:192
	v_add_u32_e32 v222, 0xd000, v218
	v_add_u32_e32 v100, 0x1000, v100
	ds_read_b128 v[218:221], v222
	ds_read_b128 v[222:225], v222 offset:64
	ds_read_b128 v[226:229], v100 offset:256
	ds_read_b128 v[230:233], v100 offset:320
	ds_read_b128 v[234:237], v100 offset:384
	ds_read_b128 v[238:241], v100 offset:448
	v_add_u32_e32 v100, 0xe000, v253
	ds_read_b128 v[242:245], v100 offset:512
	ds_read_b128 v[246:249], v100 offset:576
	s_waitcnt lgkmcnt(11)
	v_mfma_f32_16x16x32_bf16 v[60:63], v[60:63], v[84:87], 0
	s_waitcnt lgkmcnt(10)
	v_mfma_f32_16x16x32_bf16 v[60:63], v[64:67], v[88:91], v[60:63]
	v_add_u32_e32 v64, 32, v250
	v_ashrrev_i32_e32 v65, 31, v64
	v_lshlrev_b64 v[64:65], 14, v[64:65]
	s_waitcnt lgkmcnt(9)
	v_mfma_f32_16x16x32_bf16 v[60:63], v[68:71], v[92:95], v[60:63]
	v_lshl_add_u64 v[64:65], v[182:183], 0, v[64:65]
	v_cndmask_b32_e32 v69, v179, v65, vcc
	v_cndmask_b32_e32 v68, v178, v64, vcc
	s_waitcnt lgkmcnt(8)
	v_mfma_f32_16x16x32_bf16 v[60:63], v[72:75], v[96:99], v[60:63]
	v_add_co_u32_e64 v70, s[4:5], s58, v68
	s_waitcnt lgkmcnt(7)
	v_mfma_f32_16x16x32_bf16 v[60:63], v[218:221], v[76:79], v[60:63]
	v_addc_co_u32_e64 v71, s[4:5], 0, v69, s[4:5]
	s_waitcnt lgkmcnt(5)
	v_mfma_f32_16x16x32_bf16 v[64:67], v[226:229], v[84:87], 0
	v_mfma_f32_16x16x32_bf16 v[60:63], v[222:225], v[80:83], v[60:63]
	s_waitcnt lgkmcnt(4)
	v_mfma_f32_16x16x32_bf16 v[64:67], v[230:233], v[88:91], v[64:67]
	s_waitcnt lgkmcnt(3)
	v_mfma_f32_16x16x32_bf16 v[64:67], v[234:237], v[92:95], v[64:67]
	s_nop 3
	global_store_dword v[68:69], v60, off
	v_add_co_u32_e64 v60, s[4:5], s59, v68
	global_store_dword v[70:71], v61, off
	s_nop 0
	v_addc_co_u32_e64 v61, s[4:5], 0, v69, s[4:5]
	global_store_dword v[60:61], v62, off
	v_add_co_u32_e64 v60, s[4:5], s60, v68
	s_nop 1
	v_addc_co_u32_e64 v61, s[4:5], 0, v69, s[4:5]
	global_store_dword v[60:61], v63, off
	s_waitcnt lgkmcnt(2)
	v_mfma_f32_16x16x32_bf16 v[60:63], v[238:241], v[96:99], v[64:67]
	s_waitcnt lgkmcnt(1)
	v_mfma_f32_16x16x32_bf16 v[60:63], v[242:245], v[76:79], v[60:63]
	s_nop 0
	v_add_u32_e32 v64, 48, v250
	v_ashrrev_i32_e32 v65, 31, v64
	v_lshlrev_b64 v[64:65], 14, v[64:65]
	v_lshl_add_u64 v[64:65], v[182:183], 0, v[64:65]
	s_waitcnt lgkmcnt(0)
	v_mfma_f32_16x16x32_bf16 v[60:63], v[246:249], v[80:83], v[60:63]
	v_cndmask_b32_e32 v64, v180, v64, vcc
	v_cndmask_b32_e32 v65, v181, v65, vcc
	v_add_co_u32_e32 v66, vcc, s58, v64
	s_nop 1
	v_addc_co_u32_e32 v67, vcc, 0, v65, vcc
	s_nop 1
	global_store_dword v[64:65], v60, off
	v_add_co_u32_e32 v60, vcc, s59, v64
	global_store_dword v[66:67], v61, off
	s_nop 0
	v_addc_co_u32_e32 v61, vcc, 0, v65, vcc
	global_store_dword v[60:61], v62, off
	v_add_co_u32_e32 v60, vcc, s60, v64
	s_nop 1
	v_addc_co_u32_e32 v61, vcc, 0, v65, vcc
	global_store_dword v[60:61], v63, off
	v_lshl_add_u32 v100, v200, 2, s63
	v_add_u32_e32 v234, v100, v103
	v_add_u32_e32 v64, 0x8800, v234
	v_add_u32_e32 v88, 0x9000, v234
	v_add_u32_e32 v96, 0x9800, v234
	ds_read_b128 v[60:63], v64
	ds_read_b128 v[64:67], v64 offset:64
	ds_read_b128 v[68:71], v100 offset:62464
	ds_read_b128 v[72:75], v100 offset:62528
	ds_read_b128 v[84:87], v88 offset:256
	ds_read_b128 v[88:91], v88 offset:320
	ds_read_b128 v[92:95], v96 offset:512
	ds_read_b128 v[96:99], v96 offset:576
	ds_read_b128 v[218:221], v100 offset:62592
	ds_read_b128 v[222:225], v100 offset:62656
	v_add_u32_e32 v230, 0xa000, v234
	ds_read_b128 v[226:229], v230 offset:768
	ds_read_b128 v[230:233], v230 offset:832
	s_waitcnt lgkmcnt(9)
	v_pk_mul_f32 v[2:3], v[2:3], v[70:71]
	v_pk_mul_f32 v[0:1], v[0:1], v[68:69]
	s_waitcnt lgkmcnt(8)
	v_pk_mul_f32 v[6:7], v[6:7], v[74:75]
	v_pk_mul_f32 v[4:5], v[4:5], v[72:73]
	s_waitcnt lgkmcnt(3)
	v_pk_mul_f32 v[10:11], v[10:11], v[220:221]
	v_pk_mul_f32 v[8:9], v[8:9], v[218:219]
	s_waitcnt lgkmcnt(2)
	v_pk_mul_f32 v[14:15], v[14:15], v[224:225]
	v_pk_mul_f32 v[12:13], v[12:13], v[222:223]
	v_mfma_f32_16x16x32_bf16 v[0:3], v[60:63], v[76:79], v[0:3]
	v_mfma_f32_16x16x32_bf16 v[4:7], v[84:87], v[76:79], v[4:7]
	v_mfma_f32_16x16x32_bf16 v[8:11], v[92:95], v[76:79], v[8:11]
	s_waitcnt lgkmcnt(1)
	v_mfma_f32_16x16x32_bf16 v[12:15], v[226:229], v[76:79], v[12:15]
	v_mfma_f32_16x16x32_bf16 v[0:3], v[64:67], v[80:83], v[0:3]
	v_mfma_f32_16x16x32_bf16 v[4:7], v[88:91], v[80:83], v[4:7]
	v_mfma_f32_16x16x32_bf16 v[8:11], v[96:99], v[80:83], v[8:11]
	s_waitcnt lgkmcnt(0)
	v_mfma_f32_16x16x32_bf16 v[12:15], v[230:233], v[80:83], v[12:15]
	v_add_u32_e32 v64, 0xa800, v234
	v_add_u32_e32 v88, 0xb000, v234
	v_add_u32_e32 v96, 0xb800, v234
	ds_read_b128 v[60:63], v64 offset:1024
	ds_read_b128 v[64:67], v64 offset:1088
	ds_read_b128 v[68:71], v100 offset:62720
	ds_read_b128 v[72:75], v100 offset:62784
	ds_read_b128 v[84:87], v88 offset:1280
	ds_read_b128 v[88:91], v88 offset:1344
	ds_read_b128 v[92:95], v96 offset:1536
	ds_read_b128 v[96:99], v96 offset:1600
	ds_read_b128 v[218:221], v100 offset:62848
	ds_read_b128 v[222:225], v100 offset:62912
	v_add_u32_e32 v100, 0xc000, v234
	ds_read_b128 v[226:229], v100 offset:1792
	ds_read_b128 v[230:233], v100 offset:1856
	s_waitcnt lgkmcnt(9)
	v_pk_mul_f32 v[18:19], v[18:19], v[70:71]
	v_pk_mul_f32 v[16:17], v[16:17], v[68:69]
	s_waitcnt lgkmcnt(8)
	v_pk_mul_f32 v[22:23], v[22:23], v[74:75]
	v_pk_mul_f32 v[20:21], v[20:21], v[72:73]
	s_waitcnt lgkmcnt(3)
	v_pk_mul_f32 v[26:27], v[26:27], v[220:221]
	v_pk_mul_f32 v[24:25], v[24:25], v[218:219]
	s_waitcnt lgkmcnt(2)
	v_pk_mul_f32 v[30:31], v[30:31], v[224:225]
	v_pk_mul_f32 v[28:29], v[28:29], v[222:223]
	v_mfma_f32_16x16x32_bf16 v[16:19], v[60:63], v[76:79], v[16:19]
	v_mfma_f32_16x16x32_bf16 v[20:23], v[84:87], v[76:79], v[20:23]
	v_mfma_f32_16x16x32_bf16 v[24:27], v[92:95], v[76:79], v[24:27]
	s_waitcnt lgkmcnt(1)
	v_mfma_f32_16x16x32_bf16 v[28:31], v[226:229], v[76:79], v[28:31]
	v_mfma_f32_16x16x32_bf16 v[16:19], v[64:67], v[80:83], v[16:19]
	v_mfma_f32_16x16x32_bf16 v[20:23], v[88:91], v[80:83], v[20:23]
	v_mfma_f32_16x16x32_bf16 v[24:27], v[96:99], v[80:83], v[24:27]
	s_waitcnt lgkmcnt(0)
	v_mfma_f32_16x16x32_bf16 v[28:31], v[230:233], v[80:83], v[28:31]
	s_add_i32 s53, s53, 16
	s_add_i32 s22, s22, 28
	v_add_u32_e32 v126, 32, v126
	s_cmp_lg_u32 s51, s50
	v_add_u32_e32 v211, 64, v211
	s_cbranch_scc0 .LBB0_2517
	s_waitcnt vmcnt(16)
	v_lshlrev_b32_e32 v184, 16, v184
	v_lshlrev_b32_e32 v185, 16, v185
	v_lshlrev_b32_e32 v186, 16, v186
	v_lshlrev_b32_e32 v187, 16, v187
	v_lshlrev_b32_e32 v188, 16, v188
	v_lshlrev_b32_e32 v189, 16, v189
	v_lshlrev_b32_e32 v190, 16, v190
	v_lshlrev_b32_e32 v191, 16, v191
	v_lshlrev_b32_e32 v192, 16, v192
	v_lshlrev_b32_e32 v193, 16, v193
	v_lshlrev_b32_e32 v194, 16, v194
	v_lshlrev_b32_e32 v195, 16, v195
	v_lshlrev_b32_e32 v196, 16, v196
	v_lshlrev_b32_e32 v197, 16, v197
	v_lshlrev_b32_e32 v198, 16, v198
	v_lshlrev_b32_e32 v199, 16, v199
	s_andn2_b64 vcc, exec, s[42:43]
	s_cbranch_vccnz .Lm2_nomask_b
	v_cmp_gt_u32_e32 vcc, s45, v164
	s_nop 1
	v_cndmask_b32_e32 v188, 0, v188, vcc
	v_cmp_gt_u32_e32 vcc, s45, v165
	s_nop 1
	v_cndmask_b32_e32 v189, 0, v189, vcc
	v_cmp_gt_u32_e32 vcc, s45, v106
	s_nop 1
	v_cndmask_b32_e32 v190, 0, v190, vcc
	v_cmp_gt_u32_e32 vcc, s45, v107
	s_nop 1
	v_cndmask_b32_e32 v191, 0, v191, vcc
	v_cmp_gt_u32_e32 vcc, s45, v162
	s_nop 1
	v_cndmask_b32_e32 v196, 0, v196, vcc
	v_cmp_gt_u32_e32 vcc, s45, v163
	s_nop 1
	v_cndmask_b32_e32 v197, 0, v197, vcc
	v_cmp_gt_u32_e32 vcc, s45, v110
	s_nop 1
	v_cndmask_b32_e32 v198, 0, v198, vcc
	v_cmp_gt_u32_e32 vcc, s45, v111
	s_nop 1
	v_cndmask_b32_e32 v199, 0, v199, vcc
